# rwkv_prep first section: the nine global inputs fetched up front with one wait instead of six serialised round trips
# baseline (speedup 1.0000x reference)
; __device__ __forceinline__ int opaque_tid() { int t = threadIdx.x; asm volatile("" : "+v"(t)); return t; }
; __device__ __forceinline__ float bf2f(unsigned short b) { return __uint_as_float(((unsigned)b) << 16); }
; __device__ __forceinline__ void rwkv_prep_item(const Params& p, int l, int item, char* ldsraw) {
;     ...
;   const int tid = opaque_tid(), h = tid >> 6, jl = tid & 63;
;   const int tok0 = item * 16, b = tok0 >> 12, s0 = tok0 & 4095;
;   const float* mu = p.mu + l * 896;
; #pragma unroll
;   for (int i = 0; i < 4; i++) {
;     int idx = tid + 256 * i; int t = idx >> 6, c = idx & 63;
;     int col = C_RW + 768 + c; int tok = tok0 + t;
;     float cur = bf2f(P[(size_t)tok * PIN + col]);
;     float prv = (s0 + t > 0) ? bf2f(P[(size_t)(tok - 1) * PIN + col]) : 0.f;
;     float v = cur + (prv - cur) * mu[768 + c];
;     if (c < 32) { float e = __expf(2.f * v); v = 1.f - 2.f / (1.f + e); }
;     lds[t * 64 + c] = v;
;   }
.LBB0_586:
	s_and_b64 vcc, exec, s[26:27]
	s_cbranch_vccz .LBB0_617
	s_mov_b32 s3, s89
	s_lshl_b32 s2, s96, 4
	s_add_u32 s3, s46, s3
	s_addc_u32 s27, s47, 0
	s_mov_b32 s88, s89
	s_mov_b32 s28, s89
	s_mov_b32 s21, s89
	v_mov_b32_e32 v36, v198
	s_add_u32 s26, s3, 0x768000
	s_addc_u32 s27, s27, 0
	v_and_b32_e32 v39, 63, v36
	s_addk_i32 s2, 0x9000
	v_lshlrev_b32_e32 v2, 1, v39
	s_waitcnt vmcnt(3)
	v_ashrrev_i32_e32 v40, 6, v36
	v_lshl_add_u64 v[0:1], s[26:27], 0, v[2:3]
	v_add_u32_e32 v5, s2, v40
	v_mad_i64_i32 v[160:161], s[30:31], v5, s69, v[0:1]
	v_add_u32_e32 v168, 4, v5
	v_mad_i64_i32 v[162:163], s[30:31], v168, s69, v[0:1]
	v_add_u32_e32 v168, 8, v5
	v_mad_i64_i32 v[164:165], s[30:31], v168, s69, v[0:1]
	v_add_u32_e32 v168, 12, v5
	v_mad_i64_i32 v[166:167], s[30:31], v168, s69, v[0:1]
	v_lshlrev_b32_e32 v159, 2, v39
	global_load_dword v158, v159, s[22:23] offset:3072
	global_load_ushort v150, v[160:161], off offset:2688
	global_load_ushort v151, v[160:161], off offset:-1808
	global_load_ushort v152, v[162:163], off offset:2688
	global_load_ushort v153, v[162:163], off offset:-1808
	global_load_ushort v154, v[164:165], off offset:2688
	global_load_ushort v155, v[164:165], off offset:-1808
	global_load_ushort v156, v[166:167], off offset:2688
	global_load_ushort v157, v[166:167], off offset:-1808
	s_waitcnt vmcnt(0)
	v_mad_i64_i32 v[6:7], s[30:31], v5, s69, v[0:1]
	v_mov_b32_e32 v4, v150
	s_and_b32 s29, s2, 0xff0
	s_sub_i32 s3, 0, s29
	v_cmp_lt_i32_e32 vcc, s3, v40
	v_mov_b32_e32 v6, 0
	s_and_saveexec_b64 s[30:31], vcc
	s_cbranch_execz .LBB0_589
	v_add_u32_e32 v5, -1, v5
	v_mad_i64_i32 v[6:7], s[34:35], v5, s69, v[0:1]
	v_mov_b32_e32 v5, v151
	s_waitcnt vmcnt(0)
	v_lshlrev_b32_e32 v6, 16, v5
.LBB0_589:
	s_or_b64 exec, exec, s[30:31]
	v_lshlrev_b32_e32 v41, 2, v39
	s_waitcnt vmcnt(0)
	v_lshlrev_b32_e32 v5, 16, v4
	v_mov_b32_e32 v4, v158
	v_sub_f32_e32 v6, v6, v5
	v_cmp_gt_u32_e64 s[34:35], 32, v39
	s_waitcnt vmcnt(0)
	v_fmac_f32_e32 v5, v6, v4
	s_and_saveexec_b64 s[30:31], s[34:35]
	s_cbranch_execz .LBB0_591
	v_add_f32_e32 v5, v5, v5
	v_mul_f32_e32 v5, 0x3fb8aa3b, v5
	v_exp_f32_e32 v5, v5
	s_nop 0
	v_add_f32_e32 v5, 1.0, v5
	v_div_scale_f32 v6, s[36:37], v5, v5, 2.0
	v_rcp_f32_e32 v7, v6
	v_div_scale_f32 v8, vcc, 2.0, v5, 2.0
	v_fma_f32 v9, -v6, v7, 1.0
	v_fmac_f32_e32 v7, v9, v7
	v_mul_f32_e32 v9, v8, v7
	v_fma_f32 v10, -v6, v9, v8
	v_fmac_f32_e32 v9, v10, v7
	v_fma_f32 v6, -v6, v9, v8
	v_div_fmas_f32 v6, v6, v7, v9
	v_div_fixup_f32 v5, v6, v5, 2.0
	v_sub_f32_e32 v5, 1.0, v5
.LBB0_591:
	s_or_b64 exec, exec, s[30:31]
	v_add_u32_e32 v38, 0x100, v36
	v_ashrrev_i32_e32 v10, 6, v38
	v_add_u32_e32 v7, s2, v10
	v_mad_i64_i32 v[8:9], s[30:31], v7, s69, v[0:1]
	v_mov_b32_e32 v6, v152
	v_lshl_add_u32 v44, v36, 2, 0
	v_cmp_lt_i32_e32 vcc, s3, v10
	v_mov_b32_e32 v8, 0
	ds_write_b32 v44, v5
	s_and_saveexec_b64 s[30:31], vcc
	s_cbranch_execz .LBB0_593
	v_add_u32_e32 v5, -1, v7
	v_mad_i64_i32 v[8:9], s[36:37], v5, s69, v[0:1]
	v_mov_b32_e32 v5, v153
	s_waitcnt vmcnt(0)
	v_lshlrev_b32_e32 v8, 16, v5

; __device__ __forceinline__ float bf2f(unsigned short b) { return __uint_as_float(((unsigned)b) << 16); }
; __device__ __forceinline__ void rwkv_prep_item(const Params& p, int l, int item, char* ldsraw) {
;     ...
;   for (int i = 0; i < 4; i++) {
;     int idx = tid + 256 * i; int t = idx >> 6, c = idx & 63;
;     int col = C_RW + 768 + c; int tok = tok0 + t;
;     float cur = bf2f(P[(size_t)tok * PIN + col]);
;     float prv = (s0 + t > 0) ? bf2f(P[(size_t)(tok - 1) * PIN + col]) : 0.f;
;     float v = cur + (prv - cur) * mu[768 + c];
;     if (c < 32) { float e = __expf(2.f * v); v = 1.f - 2.f / (1.f + e); }
;     lds[t * 64 + c] = v;
.LBB0_595:
	s_or_b64 exec, exec, s[30:31]
	v_add_u32_e32 v42, 0x200, v36
	v_ashrrev_i32_e32 v7, 6, v42
	v_add_u32_e32 v6, s2, v7
	v_mad_i64_i32 v[8:9], s[30:31], v6, s69, v[0:1]
	ds_write_b32 v44, v5 offset:1024
	v_mov_b32_e32 v5, v154
	v_cmp_lt_i32_e32 vcc, s3, v7
	v_mov_b32_e32 v7, 0
	s_and_saveexec_b64 s[30:31], vcc
	s_cbranch_execz .LBB0_597
	v_add_u32_e32 v6, -1, v6
	v_mad_i64_i32 v[6:7], s[36:37], v6, s69, v[0:1]
	v_mov_b32_e32 v6, v155
	s_waitcnt vmcnt(0)
	v_lshlrev_b32_e32 v7, 16, v6

; __device__ __forceinline__ float bf2f(unsigned short b) { return __uint_as_float(((unsigned)b) << 16); }
; __device__ __forceinline__ void rwkv_prep_item(const Params& p, int l, int item, char* ldsraw) {
;     ...
;   for (int i = 0; i < 4; i++) {
;     int idx = tid + 256 * i; int t = idx >> 6, c = idx & 63;
;     int col = C_RW + 768 + c; int tok = tok0 + t;
;     float cur = bf2f(P[(size_t)tok * PIN + col]);
;     float prv = (s0 + t > 0) ? bf2f(P[(size_t)(tok - 1) * PIN + col]) : 0.f;
;     float v = cur + (prv - cur) * mu[768 + c];
;     if (c < 32) { float e = __expf(2.f * v); v = 1.f - 2.f / (1.f + e); }
;     lds[t * 64 + c] = v;
.LBB0_599:
	s_or_b64 exec, exec, s[30:31]
	v_add_u32_e32 v43, 0x300, v36
	v_ashrrev_i32_e32 v7, 6, v43
	v_add_u32_e32 v6, s2, v7
	v_mad_i64_i32 v[8:9], s[30:31], v6, s69, v[0:1]
	ds_write_b32 v44, v5 offset:2048
	v_mov_b32_e32 v5, v156
	v_cmp_lt_i32_e32 vcc, s3, v7
	v_mov_b32_e32 v7, 0
	s_and_saveexec_b64 s[30:31], vcc
	s_cbranch_execz .LBB0_601
	v_add_u32_e32 v6, -1, v6
	v_mad_i64_i32 v[0:1], s[36:37], v6, s69, v[0:1]
	v_mov_b32_e32 v0, v157
	s_waitcnt vmcnt(0)
	v_lshlrev_b32_e32 v7, 16, v0
